# low-rank K-slice + scan item prologue requests all chunk-0 operand rows at once instead of one dependent round trip per row pair
# baseline (speedup 1.0000x reference)
.LBB0_1123:
	s_lshl_b32 s0, s34, 12
	s_and_b32 s17, s26, 1
	s_bfe_i32 s22, s26, 0x10000
	s_and_b32 s21, s27, 3
	s_lshl_b32 s2, s34, 13
	s_add_i32 s3, s0, 0x2000
	s_and_b64 s[0:1], s[46:47], exec
	s_cselect_b32 s75, s2, s3
	s_bitcmp1_b32 s26, 0
	s_cselect_b64 s[2:3], -1, 0
	s_sub_i32 s1, s82, s78
	s_add_i32 s0, s82, -7
	s_add_i32 s12, s1, 24
	s_cmp_eq_u32 s17, 0
	s_cselect_b64 s[46:47], -1, 0
	s_and_b64 s[10:11], s[46:47], exec
	s_cselect_b32 s14, s84, s12
	s_cselect_b32 s23, 1, 6
	s_cselect_b32 s52, 2, 5
	s_cselect_b32 s20, 5, 2
	s_cselect_b32 s19, 6, 1
	s_cselect_b32 s18, 7, 0
	s_lshl_b32 s50, s48, 6
	s_add_i32 s12, s14, -1
	s_add_i32 s11, s82, -1
	s_ashr_i32 s51, s50, 31
	s_lshl_b64 s[26:27], s[50:51], 1
	s_min_i32 s12, s12, s11
	s_cmp_gt_i32 s14, 0
	s_cselect_b32 s12, s12, 0
	v_lshl_add_u64 v[0:1], v[56:57], 0, s[26:27]
	s_add_i32 s12, s12, s75
	v_mad_i64_i32 v[2:3], s[12:13], s12, v245, v[0:1]
	s_min_i32 s12, s14, s11
	s_cmp_gt_i32 s14, -1
	s_cselect_b32 s12, s12, 0
	s_add_i32 s12, s12, s75
	v_mad_i64_i32 v[2:3], s[12:13], s12, v245, v[0:1]
	s_or_b32 s12, s14, 1
	s_min_i32 s12, s12, s11
	s_cmp_gt_i32 s14, -2
	s_cselect_b32 s12, s12, 0
	s_add_i32 s12, s12, s75
	s_mul_i32 s53, s17, 0x1800000
	v_mov_b32_e32 v59, v51
	v_readlane_b32 s9, v254, 24
	s_mov_b32 s8, s29
	s_mov_b32 s1, 0
	s_mov_b32 s10, 2
	v_mad_i64_i32 v[2:3], s[12:13], s12, v245, v[0:1]
	s_or_b32 s12, s14, 2
	s_min_i32 s12, s12, s11
	s_cmp_gt_i32 s14, -3
	s_cselect_b32 s12, s12, 0
	s_add_i32 s12, s12, s75
	v_mad_i64_i32 v[2:3], s[12:13], s12, v245, v[0:1]
	s_or_b32 s12, s14, 3
	s_min_i32 s12, s12, s11
	s_cmp_gt_i32 s14, -4
	s_cselect_b32 s12, s12, 0
	s_add_i32 s12, s12, s75
	v_mad_i64_i32 v[2:3], s[12:13], s12, v245, v[0:1]
	s_or_b32 s12, s14, 4
	s_min_i32 s12, s12, s11
	s_cmp_gt_i32 s14, -5
	s_cselect_b32 s12, s12, 0
	s_add_i32 s12, s12, s75
	v_mad_i64_i32 v[2:3], s[12:13], s12, v245, v[0:1]
	s_or_b32 s12, s14, 5
	s_min_i32 s12, s12, s11
	s_cmp_gt_i32 s14, -6
	s_cselect_b32 s12, s12, 0
	s_add_i32 s12, s12, s75
	v_mad_i64_i32 v[2:3], s[12:13], s12, v245, v[0:1]
	s_or_b32 s12, s14, 6
	s_min_i32 s12, s12, s11
	s_cmp_gt_i32 s14, -7
	s_cselect_b32 s12, s12, 0
	s_add_i32 s12, s12, s75
	v_mad_i64_i32 v[2:3], s[12:13], s12, v245, v[0:1]
	s_or_b32 s12, s14, 7
	s_min_i32 s12, s12, s11
	s_cmp_gt_i32 s14, -8
	s_cselect_b32 s12, s12, 0
	s_add_i32 s12, s12, s75
	v_mad_i64_i32 v[2:3], s[12:13], s12, v245, v[0:1]
	s_add_i32 s12, s14, 8
	s_min_i32 s12, s12, s11
	s_cmp_gt_i32 s14, -9
	s_cselect_b32 s12, s12, 0
	s_add_i32 s12, s12, s75
	s_add_u32 s34, s4, s53
	s_addc_u32 s35, s5, 0
	v_mad_i64_i32 v[2:3], s[12:13], s12, v245, v[0:1]
	v_readlane_b32 s12, v253, 19
	v_readlane_b32 s13, v253, 20
	s_add_u32 s12, s12, s53
	s_addc_u32 s13, s13, 0
	s_ashr_i32 s49, s48, 31
	s_add_i32 s16, s14, s75
	s_lshl_b64 s[14:15], s[48:49], 2
	v_readlane_b32 s48, v253, 15
	v_readlane_b32 s49, v253, 16
	s_add_u32 s14, s48, s14
	s_addc_u32 s15, s49, s15
	v_lshl_add_u64 v[2:3], s[50:51], 0, v[48:49]
	v_mad_i64_i32 v[4:5], s[48:49], s16, v246, v[2:3]
	s_mul_i32 s48, s16, 24
	v_lshlrev_b64 v[4:5], 1, v[4:5]
	s_mul_hi_i32 s49, s16, 24
	s_add_u32 s48, s14, s48
	v_lshl_add_u64 v[6:7], s[12:13], 0, v[4:5]
	v_lshl_add_u64 v[4:5], s[34:35], 0, v[4:5]
	s_addc_u32 s49, s15, s49
	s_or_b32 s50, s16, 1
	v_mad_i64_i32 v[4:5], s[48:49], s50, v246, v[2:3]
	s_mul_hi_i32 s49, s50, 24
	s_mul_i32 s50, s50, 24
	v_lshlrev_b64 v[4:5], 1, v[4:5]
	s_add_u32 s48, s14, s50
	v_lshl_add_u64 v[6:7], s[12:13], 0, v[4:5]
	v_lshl_add_u64 v[4:5], s[34:35], 0, v[4:5]
	s_addc_u32 s49, s15, s49
	s_or_b32 s50, s16, 2
	v_mad_i64_i32 v[4:5], s[48:49], s50, v246, v[2:3]
	s_mul_hi_i32 s49, s50, 24
	s_mul_i32 s50, s50, 24
	v_lshlrev_b64 v[4:5], 1, v[4:5]
	s_add_u32 s48, s14, s50
	v_lshl_add_u64 v[6:7], s[12:13], 0, v[4:5]
	v_lshl_add_u64 v[4:5], s[34:35], 0, v[4:5]
	s_addc_u32 s49, s15, s49
	s_or_b32 s50, s16, 3
	v_mad_i64_i32 v[4:5], s[48:49], s50, v246, v[2:3]
	s_mul_hi_i32 s49, s50, 24
	s_mul_i32 s50, s50, 24
	v_lshlrev_b64 v[4:5], 1, v[4:5]
	s_add_u32 s48, s14, s50
	v_lshl_add_u64 v[6:7], s[12:13], 0, v[4:5]
	v_lshl_add_u64 v[4:5], s[34:35], 0, v[4:5]
	s_addc_u32 s49, s15, s49
	s_or_b32 s50, s16, 4
	v_mad_i64_i32 v[4:5], s[48:49], s50, v246, v[2:3]
	s_mul_hi_i32 s49, s50, 24
	s_mul_i32 s50, s50, 24
	v_lshlrev_b64 v[4:5], 1, v[4:5]
	s_add_u32 s48, s14, s50
	v_lshl_add_u64 v[6:7], s[12:13], 0, v[4:5]
	v_lshl_add_u64 v[4:5], s[34:35], 0, v[4:5]
	s_addc_u32 s49, s15, s49
	s_or_b32 s50, s16, 5
	v_mad_i64_i32 v[4:5], s[48:49], s50, v246, v[2:3]
	s_mul_hi_i32 s49, s50, 24
	s_mul_i32 s50, s50, 24
	v_lshlrev_b64 v[4:5], 1, v[4:5]
	s_add_u32 s48, s14, s50
	v_lshl_add_u64 v[6:7], s[12:13], 0, v[4:5]
	v_lshl_add_u64 v[4:5], s[34:35], 0, v[4:5]
	s_addc_u32 s49, s15, s49
	s_or_b32 s50, s16, 6
	v_mad_i64_i32 v[4:5], s[48:49], s50, v246, v[2:3]
	s_mul_hi_i32 s49, s50, 24
	s_mul_i32 s50, s50, 24
	v_lshlrev_b64 v[4:5], 1, v[4:5]
	s_add_u32 s48, s14, s50
	v_lshl_add_u64 v[6:7], s[12:13], 0, v[4:5]
	v_lshl_add_u64 v[4:5], s[34:35], 0, v[4:5]
	s_addc_u32 s49, s15, s49
	s_or_b32 s16, s16, 7
	v_mad_i64_i32 v[4:5], s[48:49], s16, v246, v[2:3]
	s_mul_hi_i32 s49, s16, 24
	s_mul_i32 s16, s16, 24
	v_lshlrev_b64 v[4:5], 1, v[4:5]
	s_add_u32 s48, s14, s16
	v_lshl_add_u64 v[6:7], s[12:13], 0, v[4:5]
	v_lshl_add_u64 v[4:5], s[34:35], 0, v[4:5]
	s_addc_u32 s49, s15, s49
	s_add_i32 s16, s82, -8
	s_and_b32 s22, s22, 7
	v_readlane_b32 s48, v253, 28
	v_readlane_b32 s49, v253, 29
	s_add_u32 s48, s48, s53
	s_addc_u32 s49, s49, 0
	s_add_u32 s26, s48, s26
	s_addc_u32 s27, s49, s27
	s_lshl_b32 s48, s21, 5
	s_add_u32 s26, s26, s48
	s_addc_u32 s27, s27, 0
	v_lshl_add_u64 v[4:5], s[26:27], 0, v[58:59]
	s_add_i32 s26, s17, s81
	s_add_i32 s27, s26, 3
	s_sub_i32 s17, s81, s17
	v_cmp_eq_u32_e64 s[48:49], s21, v61
	s_or_b32 s21, s22, s81
	s_or_b32 s22, s23, s81
	s_or_b32 s23, s52, s81
	v_lshl_add_u32 v9, s27, 6, v48
	v_lshl_add_u32 v33, s27, 8, v69
	s_add_i32 s27, s17, 4
	s_or_b32 s20, s20, s81
	s_or_b32 s19, s19, s81
	s_or_b32 s18, s18, s81
	v_lshl_add_u32 v6, s21, 6, v48
	v_lshl_add_u32 v27, s21, 8, v69
	s_lshl_b32 s21, s21, 2
	v_lshl_add_u32 v7, s22, 6, v48
	v_lshl_add_u32 v29, s22, 8, v69
	s_lshl_b32 s22, s22, 2
	v_lshl_add_u32 v8, s23, 6, v48
	v_lshl_add_u32 v31, s23, 8, v69
	s_lshl_b32 s23, s23, 2
	s_lshl_b32 s26, s26, 2
	v_lshl_add_u32 v10, s27, 6, v48
	s_lshl_b32 s17, s17, 2
	v_lshl_add_u32 v11, s20, 6, v48
	v_lshl_add_u32 v37, s20, 8, v69
	s_lshl_b32 s20, s20, 2
	v_lshl_add_u32 v12, s19, 6, v48
	v_lshl_add_u32 v39, s19, 8, v69
	s_lshl_b32 s19, s19, 2
	v_lshl_add_u32 v13, s18, 6, v48
	v_lshl_add_u32 v41, s18, 8, v69
	s_lshl_b32 s18, s18, 2
	v_add_u32_e32 v28, s21, v70
	v_add_u32_e32 v30, s22, v70
	v_add_u32_e32 v32, s23, v70
	v_add_u32_e32 v34, s26, v70
	v_lshl_add_u32 v35, s27, 8, v69
	v_add_u32_e32 v36, s17, v70
	v_add_u32_e32 v38, s20, v70
	v_add_u32_e32 v40, s19, v70
	v_add_u32_e32 v43, s18, v70
	v_lshl_add_u32 v44, v6, 2, s9
	v_add_u32_e32 v45, s21, v71
	v_lshl_add_u32 v46, v7, 2, s9
	v_add_u32_e32 v47, s22, v71
	v_lshl_add_u32 v50, v8, 2, s9
	v_add_u32_e32 v52, s23, v71
	v_lshl_add_u32 v53, v9, 2, s9
	v_add_u32_e32 v59, s26, v71
	v_lshl_add_u32 v79, v10, 2, s9
	v_add_u32_e32 v80, s17, v71
	v_lshl_add_u32 v81, v11, 2, s9
	v_add_u32_e32 v82, s20, v71
	v_lshl_add_u32 v83, v12, 2, s9
	v_add_u32_e32 v84, s19, v71
	v_lshl_add_u32 v85, v13, 2, s9
	v_add_u32_e32 v86, s18, v71
	s_movk_i32 s17, 0xfe00
	s_mov_b32 s19, 0
	s_lshl_b32 s19, s19, 5
	s_add_i32 s19, s84, s19
	s_not_b32 s20, s19
	s_add_i32 s22, s0, s20
	s_and_b64 s[20:21], s[46:47], exec
	s_cselect_b32 s19, s19, s22
	s_add_i32 s20, s19, -1
	s_min_i32 s20, s20, s11
	s_cmp_gt_i32 s19, 0
	s_cselect_b32 s20, s20, 0
	s_add_i32 s20, s20, s75
	v_mad_i64_i32 v[88:89], s[20:21], s20, v245, v[0:1]
	s_min_i32 s20, s19, s11
	s_cmp_gt_i32 s19, -1
	s_cselect_b32 s20, s20, 0
	s_add_i32 s20, s20, s75
	v_mad_i64_i32 v[96:97], s[20:21], s20, v245, v[0:1]
	s_or_b32 s20, s19, 1
	s_min_i32 s20, s20, s11
	s_cmp_gt_i32 s19, -2
	s_cselect_b32 s20, s20, 0
	s_add_i32 s20, s20, s75
	v_mad_i64_i32 v[104:105], s[20:21], s20, v245, v[0:1]
	s_or_b32 s20, s19, 2
	s_min_i32 s20, s20, s11
	s_cmp_gt_i32 s19, -3
	s_cselect_b32 s20, s20, 0
	s_add_i32 s20, s20, s75
	v_mad_i64_i32 v[114:115], s[20:21], s20, v245, v[0:1]
	s_or_b32 s20, s19, 3
	s_min_i32 s20, s20, s11
	s_cmp_gt_i32 s19, -4
	s_cselect_b32 s20, s20, 0
	s_add_i32 s20, s20, s75
	global_load_ushort v90, v[88:89], off
	global_load_ushort v91, v[88:89], off offset:768
	s_nop 0
	global_load_ushort v89, v[88:89], off offset:1536
	s_nop 0
	global_load_ushort v92, v[96:97], off
	global_load_ushort v94, v[96:97], off offset:768
	s_nop 0
	global_load_ushort v96, v[96:97], off offset:1536
	s_nop 0
	global_load_ushort v97, v[104:105], off
	global_load_ushort v98, v[104:105], off offset:768
	global_load_ushort v100, v[104:105], off offset:1536
	global_load_ushort v103, v[114:115], off
	s_nop 0
	global_load_ushort v104, v[114:115], off offset:768
	global_load_ushort v105, v[114:115], off offset:1536
	v_mad_i64_i32 v[114:115], s[20:21], s20, v245, v[0:1]
	s_or_b32 s20, s19, 4
	s_min_i32 s20, s20, s11
	s_cmp_gt_i32 s19, -5
	s_cselect_b32 s20, s20, 0
	s_add_i32 s20, s20, s75
	v_mad_i64_i32 v[118:119], s[20:21], s20, v245, v[0:1]
	s_or_b32 s20, s19, 5
	s_min_i32 s20, s20, s11
	s_cmp_gt_i32 s19, -6
	s_cselect_b32 s20, s20, 0
	s_add_i32 s20, s20, s75
	v_mad_i64_i32 v[122:123], s[20:21], s20, v245, v[0:1]
	s_or_b32 s20, s19, 6
	s_min_i32 s20, s20, s11
	s_cmp_gt_i32 s19, -7
	s_cselect_b32 s20, s20, 0
	s_add_i32 s20, s20, s75
	v_mad_i64_i32 v[124:125], s[20:21], s20, v245, v[0:1]
	s_or_b32 s20, s19, 7
	s_min_i32 s20, s20, s11
	s_cmp_gt_i32 s19, -8
	s_cselect_b32 s20, s20, 0
	s_add_i32 s20, s20, s75
	v_mad_i64_i32 v[128:129], s[20:21], s20, v245, v[0:1]
	s_add_i32 s20, s19, 8
	s_min_i32 s20, s20, s11
	s_cmp_gt_i32 s19, -9
	s_cselect_b32 s20, s20, 0
	s_add_i32 s20, s20, s75
	s_add_i32 s19, s19, s75
	v_mad_i64_i32 v[130:131], s[20:21], s20, v245, v[0:1]
	v_mad_i64_i32 v[132:133], s[20:21], s19, v246, v[2:3]
	s_mul_i32 s22, s19, 24
	v_lshlrev_b64 v[132:133], 1, v[132:133]
	s_mul_hi_i32 s21, s19, 24
	s_add_u32 s20, s14, s22
	v_lshl_add_u64 v[134:135], s[12:13], 0, v[132:133]
	v_lshl_add_u64 v[132:133], s[34:35], 0, v[132:133]
	s_addc_u32 s21, s15, s21
	s_add_i32 s23, s19, 1
	global_load_ushort v109, v[114:115], off
	global_load_ushort v113, v[114:115], off offset:768
	s_nop 0
	global_load_ushort v114, v[114:115], off offset:1536
	s_nop 0
	global_load_ushort v115, v[118:119], off
	global_load_ushort v116, v[118:119], off offset:768
	global_load_ushort v117, v[118:119], off offset:1536
	s_nop 0
	global_load_ushort v118, v[122:123], off
	global_load_ushort v119, v[122:123], off offset:768
	global_load_ushort v121, v[122:123], off offset:1536
	s_nop 0
	global_load_ushort v122, v[124:125], off
	global_load_ushort v123, v[124:125], off offset:768
	s_nop 0
	global_load_ushort v124, v[124:125], off offset:1536
	s_nop 0
	global_load_ushort v125, v[128:129], off
	global_load_ushort v126, v[128:129], off offset:768
	global_load_ushort v127, v[128:129], off offset:1536
	s_nop 0
	global_load_ushort v128, v[130:131], off
	global_load_ushort v129, v[130:131], off offset:768
	s_nop 0
	global_load_ushort v130, v[130:131], off offset:1536
	global_load_ushort v131, v[134:135], off
	global_load_dword v26, v51, s[20:21]
	global_load_ushort v132, v[132:133], off
	v_mad_i64_i32 v[134:135], s[20:21], s23, v246, v[2:3]
	s_add_i32 s20, s22, 24
	v_lshlrev_b64 v[134:135], 1, v[134:135]
	s_mul_hi_i32 s21, s23, 24
	s_add_u32 s20, s14, s20
	v_lshl_add_u64 v[164:165], s[12:13], 0, v[134:135]
	v_lshl_add_u64 v[134:135], s[34:35], 0, v[134:135]
	s_addc_u32 s21, s15, s21
	s_add_i32 s23, s19, 2
	global_load_ushort v133, v[164:165], off
	global_load_dword v42, v51, s[20:21]
	global_load_ushort v134, v[134:135], off
	v_mad_i64_i32 v[164:165], s[20:21], s23, v246, v[2:3]
	s_add_i32 s20, s22, 48
	v_lshlrev_b64 v[164:165], 1, v[164:165]
	s_mul_hi_i32 s21, s23, 24
	s_add_u32 s20, s14, s20
	v_lshl_add_u64 v[166:167], s[12:13], 0, v[164:165]
	v_lshl_add_u64 v[164:165], s[34:35], 0, v[164:165]
	s_addc_u32 s21, s15, s21
	s_add_i32 s23, s19, 3
	global_load_ushort v135, v[166:167], off
	global_load_ushort v136, v[164:165], off
	global_load_dword v87, v51, s[20:21]
	v_mad_i64_i32 v[164:165], s[20:21], s23, v246, v[2:3]
	s_add_i32 s20, s22, 0x48
	v_lshlrev_b64 v[164:165], 1, v[164:165]
	s_mul_hi_i32 s21, s23, 24
	s_add_u32 s20, s14, s20
	v_lshl_add_u64 v[166:167], s[12:13], 0, v[164:165]
	v_lshl_add_u64 v[164:165], s[34:35], 0, v[164:165]
	s_addc_u32 s21, s15, s21
	s_add_i32 s23, s19, 4
	global_load_ushort v163, v[166:167], off
	global_load_dword v88, v51, s[20:21]
	global_load_ushort v164, v[164:165], off
	v_mad_i64_i32 v[166:167], s[20:21], s23, v246, v[2:3]
	s_add_i32 s20, s22, 0x60
	v_lshlrev_b64 v[166:167], 1, v[166:167]
	s_mul_hi_i32 s21, s23, 24
	s_add_u32 s20, s14, s20
	v_lshl_add_u64 v[168:169], s[12:13], 0, v[166:167]
	v_lshl_add_u64 v[166:167], s[34:35], 0, v[166:167]
	s_addc_u32 s21, s15, s21
	s_add_i32 s23, s19, 5
	global_load_ushort v165, v[168:169], off
	global_load_dword v93, v51, s[20:21]
	global_load_ushort v166, v[166:167], off
	v_mad_i64_i32 v[168:169], s[20:21], s23, v246, v[2:3]
	s_add_i32 s20, s22, 0x78
	v_lshlrev_b64 v[168:169], 1, v[168:169]
	s_mul_hi_i32 s21, s23, 24
	s_add_u32 s20, s14, s20
	v_lshl_add_u64 v[170:171], s[12:13], 0, v[168:169]
	v_lshl_add_u64 v[168:169], s[34:35], 0, v[168:169]
	s_addc_u32 s21, s15, s21
	s_add_i32 s23, s19, 6
	global_load_ushort v167, v[170:171], off
	global_load_dword v95, v51, s[20:21]
	global_load_ushort v168, v[168:169], off
	v_mad_i64_i32 v[170:171], s[20:21], s23, v246, v[2:3]
	s_add_i32 s20, s22, 0x90
	v_lshlrev_b64 v[170:171], 1, v[170:171]
	s_mul_hi_i32 s21, s23, 24
	s_add_u32 s20, s14, s20
	v_lshl_add_u64 v[172:173], s[12:13], 0, v[170:171]
	v_lshl_add_u64 v[170:171], s[34:35], 0, v[170:171]
	s_addc_u32 s21, s15, s21
	s_add_i32 s19, s19, 7
	global_load_ushort v169, v[172:173], off
	global_load_dword v99, v51, s[20:21]
	s_addk_i32 s22, 0xa8
	global_load_ushort v170, v[170:171], off
	v_mad_i64_i32 v[172:173], s[20:21], s19, v246, v[2:3]
	v_lshlrev_b64 v[172:173], 1, v[172:173]
	s_mul_hi_i32 s19, s19, 24
	s_add_u32 s20, s14, s22
	v_lshl_add_u64 v[174:175], s[12:13], 0, v[172:173]
	v_lshl_add_u64 v[172:173], s[34:35], 0, v[172:173]
	s_addc_u32 s21, s15, s19
	global_load_ushort v171, v[174:175], off
	global_load_dword v107, v51, s[20:21]
	s_add_i32 s20, s36, s82
	global_load_ushort v172, v[172:173], off
	s_waitcnt vmcnt(0)
	v_and_b32_e32 v89, 0xffff, v89
	v_perm_b32 v90, v92, v90, s33
	v_perm_b32 v91, v94, v91, s33
	v_and_b32_e32 v92, 0xffff, v96
	v_and_b32_e32 v94, 0xffff, v100
	v_perm_b32 v96, v103, v97, s33
	v_perm_b32 v97, v104, v98, s33
	v_and_b32_e32 v98, 0xffff, v105
	v_and_b32_e32 v100, 0xffff, v114
	v_perm_b32 v103, v115, v109, s33
	v_perm_b32 v104, v116, v113, s33
	v_and_b32_e32 v105, 0xffff, v117
	v_and_b32_e32 v109, 0xffff, v121
	v_perm_b32 v113, v122, v118, s33
	v_perm_b32 v114, v123, v119, s33
	v_and_b32_e32 v115, 0xffff, v124
	v_and_b32_e32 v116, 0xffff, v127
	v_perm_b32 v117, v128, v125, s33
	v_perm_b32 v118, v129, v126, s33
	v_and_b32_e32 v119, 0xffff, v130
	v_and_b32_e32 v121, 0xffff, v131
	v_and_b32_e32 v122, 0xffff, v132
	v_and_b32_e32 v123, 0xffff, v133
	v_and_b32_e32 v124, 0xffff, v134
	v_and_b32_e32 v125, 0xffff, v135
	v_and_b32_e32 v126, 0xffff, v136
	v_and_b32_e32 v127, 0xffff, v163
	v_and_b32_e32 v128, 0xffff, v164
	v_and_b32_e32 v129, 0xffff, v165
	v_and_b32_e32 v130, 0xffff, v166
	v_and_b32_e32 v131, 0xffff, v167
	v_and_b32_e32 v132, 0xffff, v168
	v_and_b32_e32 v133, 0xffff, v169
	v_and_b32_e32 v134, 0xffff, v170
	v_and_b32_e32 v135, 0xffff, v171
	v_and_b32_e32 v136, 0xffff, v172
	s_branch .LBB0_1126
